# grid barrier main path hand-written: XCD leader bumps the global arrive counter without waiting for a return, all workgroups poll that counter (no generation words, no leader relay)
# speedup vs baseline: 1.0099x; 1.0099x over previous
.LBB0_112:
	s_or_b64 exec, exec, s[10:11]
	v_cvt_f32_u32_e32 v4, v2
	s_waitcnt vmcnt(0)
	v_readfirstlane_b32 s3, v3
	v_sub_u32_e32 v3, 0, v2
	v_rcp_iflag_f32_e32 v4, v4
	v_add_u32_e32 v5, s3, v1
	v_mul_f32_e32 v4, 0x4f7ffffe, v4
	v_cvt_u32_f32_e32 v4, v4
	v_mul_lo_u32 v1, v3, v4
	v_mul_hi_u32 v1, v4, v1
	v_add_u32_e32 v1, v4, v1
	v_mul_hi_u32 v1, v5, v1
	v_mul_lo_u32 v3, v1, v2
	v_sub_u32_e32 v3, v5, v3
	v_add_u32_e32 v4, 1, v1
	v_cmp_ge_u32_e32 vcc, v3, v2
	s_nop 1
	v_cndmask_b32_e32 v1, v1, v4, vcc
	v_sub_u32_e32 v4, v3, v2
	v_cndmask_b32_e32 v3, v3, v4, vcc
	v_add_u32_e32 v4, 1, v1
	v_cmp_ge_u32_e32 vcc, v3, v2
	v_add_u32_e32 v3, 1, v5
	s_nop 0
	v_cndmask_b32_e32 v1, v1, v4, vcc
	v_mul_lo_u32 v4, v2, v1
	v_add_u32_e32 v2, v4, v2
	v_cmp_ne_u32_e32 vcc, v3, v2
	s_waitcnt lgkmcnt(0)
	v_add_u32_e32 v1, 1, v1
	v_mul_lo_u32 v1, v1, v0
	s_cbranch_vccnz .Lgb1_poll
	buffer_wbl2 sc1
	s_waitcnt vmcnt(0)
	v_mov_b32_e32 v2, 0x3000
	v_mov_b32_e32 v3, 1
	global_atomic_add v2, v3, s[48:49] offset:1024
.Lgb1_poll:
	v_mov_b32_e32 v2, 0x3000
.Lgb1_loop:
	global_load_dword v3, v2, s[48:49] offset:1024 sc1
	s_waitcnt vmcnt(0)
	v_cmp_lt_u32_e32 vcc, v3, v1
	s_cbranch_vccz .Lgb1_done
	s_sleep 1
	s_branch .Lgb1_loop
.Lgb1_done:
	buffer_inv sc1
	s_waitcnt vmcnt(0)

.LBB0_1477:
	s_or_b64 exec, exec, s[6:7]
	v_cvt_f32_u32_e32 v4, v2
	s_waitcnt vmcnt(0)
	v_readfirstlane_b32 s4, v3
	v_sub_u32_e32 v3, 0, v2
	v_rcp_iflag_f32_e32 v4, v4
	v_add_u32_e32 v5, s4, v1
	v_mul_f32_e32 v4, 0x4f7ffffe, v4
	v_cvt_u32_f32_e32 v4, v4
	v_mul_lo_u32 v1, v3, v4
	v_mul_hi_u32 v1, v4, v1
	v_add_u32_e32 v1, v4, v1
	v_mul_hi_u32 v1, v5, v1
	v_mul_lo_u32 v3, v1, v2
	v_sub_u32_e32 v3, v5, v3
	v_add_u32_e32 v4, 1, v1
	v_cmp_ge_u32_e32 vcc, v3, v2
	s_nop 1
	v_cndmask_b32_e32 v1, v1, v4, vcc
	v_sub_u32_e32 v4, v3, v2
	v_cndmask_b32_e32 v3, v3, v4, vcc
	v_add_u32_e32 v4, 1, v1
	v_cmp_ge_u32_e32 vcc, v3, v2
	v_add_u32_e32 v3, 1, v5
	s_nop 0
	v_cndmask_b32_e32 v1, v1, v4, vcc
	v_mul_lo_u32 v4, v2, v1
	v_add_u32_e32 v2, v4, v2
	v_cmp_ne_u32_e32 vcc, v3, v2
	s_waitcnt lgkmcnt(0)
	v_add_u32_e32 v1, 1, v1
	v_mul_lo_u32 v1, v1, v0
	s_cbranch_vccnz .Lgb17_poll
	buffer_wbl2 sc1
	s_waitcnt vmcnt(0)
	v_mov_b32_e32 v2, 0x3000
	v_mov_b32_e32 v3, 1
	global_atomic_add v2, v3, s[48:49] offset:1024
